# attention step: waves 4-7 run softmax+PV(j) before QK(j+1) (waves 0-3 keep QK first) so SIMD partners use different pipes
# baseline (speedup 1.0000x reference)
.LBB0_189:
	s_cmp_gt_i32 s27, 1
	s_mov_b64 s[6:7], -1
	s_cbranch_scc0 .LBB0_345
	s_cmp_gt_i32 s27, 2
	s_cbranch_scc0 .LBB0_233
	s_cmp_lt_i32 s94, 19
	s_cbranch_scc1 .LBB0_232
	v_writelane_b32 v255, s27, 36
	s_mov_b32 s4, s18
	v_writelane_b32 v255, s4, 34
	s_add_i32 s8, s18, -2
	v_bfe_u32 v198, v168, 5, 1
	v_writelane_b32 v255, s5, 35
	s_lshl_b32 s4, s8, 1
	s_lshl_b64 s[6:7], s[4:5], 2
	s_add_u32 s6, s88, s6
	s_addc_u32 s7, s89, s7
	global_load_dwordx2 v[170:171], v161, s[6:7] offset:64
	s_lshl_b32 s4, s8, 4
	s_lshl_b64 s[6:7], s[4:5], 2
	s_add_u32 s6, s88, s6
	s_addc_u32 s7, s89, s7
	v_writelane_b32 v255, s6, 37
	v_readlane_b32 s4, v253, 14
	v_readlane_b32 s12, v252, 19
	v_writelane_b32 v255, s7, 38
	v_ashrrev_i32_e32 v200, 4, v166
	v_readlane_b32 s6, v255, 29
	s_cmp_lt_i32 s6, s4
	s_cselect_b64 s[84:85], -1, 0
	s_cmp_ge_i32 s6, s4
	s_cselect_b64 s[6:7], -1, 0
	s_lshl_b32 s4, s8, 7
	s_lshl_b64 s[8:9], s[4:5], 2
	v_and_b32_e32 v4, 15, v168
	v_lshlrev_b32_e32 v5, 4, v168
	v_readlane_b32 s10, v252, 42
	s_movk_i32 s4, 0x110
	v_lshlrev_b32_e32 v160, 4, v198
	v_readlane_b32 s22, v252, 29
	s_waitcnt lgkmcnt(0)
	v_and_b32_e32 v1, 63, v168
	v_ashrrev_i32_e32 v2, 8, v166
	v_lshlrev_b32_e32 v0, 3, v4
	v_and_b32_e32 v174, 0x70, v5
	v_mov_b32_e32 v175, v161
	v_readlane_b32 s11, v252, 43
	v_lshlrev_b32_e32 v4, 4, v4
	v_mul_lo_u32 v6, v200, s4
	v_lshlrev_b32_e32 v201, 3, v168
	v_add_u32_e32 v202, 0, v160
	v_xor_b32_e32 v8, 32, v220
	v_readlane_b32 s20, v252, 27
	v_readlane_b32 s21, v252, 28
	v_readlane_b32 s23, v252, 30
	s_add_u32 s8, s22, s8
	v_and_b32_e32 v181, 31, v168
	v_bfe_u32 v3, v166, 6, 2
	v_lshlrev_b32_e32 v176, 6, v2
	v_ashrrev_i32_e32 v178, 3, v166
	v_lshl_add_u64 v[182:183], s[10:11], 0, v[174:175]
	v_add3_u32 v175, 0, v4, v6
	v_and_b32_e32 v4, 0x60, v5
	v_and_b32_e32 v5, 8, v201
	s_movk_i32 s4, 0x90
	v_lshl_add_u32 v203, v2, 7, v202
	v_readlane_b32 s10, v254, 41
	v_mov_b32_e32 v7, 0x3600
	v_cmp_lt_i32_e32 vcc, v8, v221
	v_cmp_eq_u32_e64 s[38:39], 1, v2
	v_lshl_add_u32 v1, v1, 2, 0
	v_lshlrev_b32_e32 v2, 8, v166
	v_readlane_b32 s20, v255, 17
	s_addc_u32 s9, s23, s9
	v_lshlrev_b32_e32 v199, 5, v3
	v_lshlrev_b32_e32 v172, 3, v198
	v_add3_u32 v6, 0, v4, v5
	v_mul_lo_u32 v167, v178, s4
	v_add3_u32 v4, s10, v4, v5
	v_add_u32_e32 v5, s10, v160
	v_mul_u32_u24_e32 v169, 0x90, v181
	v_mad_u32_u24 v7, v181, s4, v7
	v_cndmask_b32_e32 v8, v220, v8, vcc
	v_lshl_add_u32 v205, v3, 14, v1
	s_movk_i32 s4, 0x100
	v_and_b32_e32 v3, 0xc000, v2
	v_or_b32_e32 v2, 0x3f00, v2
	v_cmp_eq_u32_e64 s[36:37], 0, v166
	v_readlane_b32 s21, v255, 18
	v_ashrrev_i32_e32 v177, 31, v176
	v_ashrrev_i32_e32 v179, 31, v178
	v_mul_u32_u24_e32 v204, 0x110, v181
	v_lshlrev_b32_e32 v180, 2, v198
	v_lshlrev_b32_e32 v173, 2, v8
	v_cmp_gt_u32_e64 s[40:41], s4, v166
	v_add_u32_e32 v206, v1, v3
	v_lshl_add_u64 v[184:185], s[8:9], 0, v[160:161]
	s_mov_b64 s[8:9], -1
	s_waitcnt vmcnt(0)
	v_mov_b32_e32 v186, v170
	v_mov_b32_e32 v187, v170
	v_add_u32_e32 v207, v202, v7
	v_add_u32_e32 v208, v4, v167
	v_add_u32_e32 v209, v5, v169
	v_add_u32_e32 v210, v1, v2
	v_lshlrev_b32_e32 v188, 1, v172
	v_lshlrev_b32_e32 v190, 1, v0
	v_add_u32_e32 v211, v6, v167
	v_readlane_b32 s13, v252, 20
	v_readlane_b32 s14, v252, 21
	v_readlane_b32 s15, v252, 22
	v_readlane_b32 s16, v252, 23
	v_readlane_b32 s17, v252, 24
	v_readlane_b32 s18, v252, 25
	v_readlane_b32 s19, v252, 26
	v_readlane_b32 s24, v252, 31
	v_readlane_b32 s25, v252, 32
	v_readlane_b32 s26, v252, 33
	v_readlane_b32 s27, v252, 34
	v_readlane_b32 s99, v253, 8
	s_lshr_b32 s99, s99, 2
	s_branch .LBB0_194

.LBB0_204:
	s_or_b64 exec, exec, s[6:7]
	s_cmp_eq_u32 s99, 0
	s_cbranch_scc0 .Lda2_qk
.Lda2_stage:
	s_add_i32 s4, s16, 1
	s_cmp_lg_u32 s16, 2
	s_cselect_b32 s24, s4, 0
	s_mul_i32 s4, s24, 0x4400
	v_add_u32_e32 v162, s4, v175
	s_add_i32 s4, s24, 1
	s_cmp_lg_u32 s24, 2
	s_cselect_b32 s16, s4, 0
	s_add_i32 s15, s15, 2
	s_addk_i32 s13, 0x80
	s_cmp_ge_u32 s17, s12
	s_waitcnt vmcnt(3)
	ds_write_b128 v162, v[144:147]
	s_waitcnt vmcnt(2)
	ds_write_b128 v162, v[148:151] offset:8704
	s_waitcnt vmcnt(1)
	ds_write2_b64 v189, v[156:157], v[158:159] offset0:128 offset1:130
	s_waitcnt vmcnt(0)
	ds_write2_b64 v191, v[152:153], v[154:155] offset1:2
	s_waitcnt lgkmcnt(0)
	s_barrier
	s_cbranch_scc1 .LBB0_220
.LBB0_205:
	s_add_i32 s17, s15, -1
	s_cmp_lt_u32 s17, s12
	s_cselect_b64 s[6:7], -1, 0
	s_and_b64 s[8:9], s[6:7], exec
	s_cselect_b32 s4, s17, s14
	s_lshl_b32 s4, s4, 6
	s_add_i32 s18, s15, -2
	s_or_b32 s19, s4, 32
	s_cmp_lt_u32 s18, s12
	s_cselect_b64 s[8:9], -1, 0
	v_mad_u64_u32 v[144:145], s[10:11], s4, v228, v[194:195]
	v_mad_u64_u32 v[148:149], s[10:11], s19, v228, v[194:195]
	s_and_b64 s[10:11], s[8:9], exec
	s_cselect_b32 s10, s18, s14
	s_lshl_b32 s10, s10, 6
	s_mov_b32 s11, s5
	v_lshl_add_u64 v[152:153], s[10:11], 1, v[196:197]
	v_add_co_u32_e32 v154, vcc, 0x80000, v152
	global_load_dwordx4 v[144:147], v[144:145], off
	s_nop 0
	global_load_dwordx4 v[148:151], v[148:149], off
	v_addc_co_u32_e32 v155, vcc, 0, v153, vcc
	global_load_dwordx4 v[156:159], v[152:153], off
	s_nop 0
	global_load_dwordx4 v[152:155], v[154:155], off
	s_sub_i32 s10, s13, 30
	v_cmp_le_u32_e32 vcc, s10, v212
	s_and_b64 s[100:101], s[8:9], vcc
	s_cmp_eq_u32 s99, 0
	s_cbranch_scc0 .Lda1_soft
.Lda1_qk:
	s_and_saveexec_b64 s[8:9], s[100:101]
	s_cbranch_execz .LBB0_207
	s_mul_i32 s10, s24, 0x4400
	s_setprio 1
	v_add3_u32 v162, v203, s10, v204
	ds_read_b128 v[112:115], v162
	ds_read_b128 v[116:119], v162 offset:32
	ds_read_b128 v[120:123], v162 offset:64
	ds_read_b128 v[124:127], v162 offset:96
	ds_read_b128 v[222:225], v162 offset:8704
	ds_read_b128 v[236:239], v162 offset:8736
	ds_read_b128 v[240:243], v162 offset:8768
	ds_read_b128 v[244:247], v162 offset:8800
	s_waitcnt lgkmcnt(7)
	v_mfma_f32_32x32x16_bf16 v[96:111], v[112:115], v[128:131], 0
	s_waitcnt lgkmcnt(6)
	v_mfma_f32_32x32x16_bf16 v[96:111], v[116:119], v[132:135], v[96:111]
	s_waitcnt lgkmcnt(5)
	v_mfma_f32_32x32x16_bf16 v[96:111], v[120:123], v[136:139], v[96:111]
	s_waitcnt lgkmcnt(4)
	v_mfma_f32_32x32x16_bf16 v[96:111], v[124:127], v[140:143], v[96:111]
	s_waitcnt lgkmcnt(3)
	v_mfma_f32_32x32x16_bf16 v[112:127], v[222:225], v[128:131], 0
	s_waitcnt lgkmcnt(2)
	v_mfma_f32_32x32x16_bf16 v[112:127], v[236:239], v[132:135], v[112:127]
	s_waitcnt lgkmcnt(1)
	v_mfma_f32_32x32x16_bf16 v[112:127], v[240:243], v[136:139], v[112:127]
	s_waitcnt lgkmcnt(0)
	v_mfma_f32_32x32x16_bf16 v[112:127], v[244:247], v[140:143], v[112:127]
	s_setprio 0
.LBB0_207:
	s_or_b64 exec, exec, s[8:9]
	s_cmp_eq_u32 s99, 0
	s_cbranch_scc0 .Lda1_stage
.Lda1_soft:
	s_sub_i32 s8, s13, 63
	v_cmp_le_u32_e32 vcc, s8, v214
	s_and_saveexec_b64 s[8:9], vcc
	s_cbranch_execz .LBB0_213
	v_cmp_gt_u32_e32 vcc, s13, v212
	s_and_saveexec_b64 s[10:11], vcc
	s_cbranch_execz .LBB0_210
	v_add_u32_e32 v162, s13, v180
	v_subrev_u32_e32 v163, 63, v162
	v_cmp_le_u32_e32 vcc, v163, v213
	s_nop 1
	v_cndmask_b32_e32 v64, v229, v64, vcc
	v_cmp_lt_u32_e32 vcc, v163, v213
	v_subrev_u32_e32 v163, 61, v162
	s_nop 0
	v_cndmask_b32_e32 v65, v229, v65, vcc
	v_cmp_le_u32_e32 vcc, v163, v213
	v_subrev_u32_e32 v163, 60, v162
	s_nop 0
	v_cndmask_b32_e32 v66, v229, v66, vcc
	v_cmp_le_u32_e32 vcc, v163, v213
	v_subrev_u32_e32 v163, 55, v162
	s_nop 0
	v_cndmask_b32_e32 v67, v229, v67, vcc
	v_cmp_le_u32_e32 vcc, v163, v213
	v_subrev_u32_e32 v163, 54, v162
	s_nop 0
	v_cndmask_b32_e32 v68, v229, v68, vcc
	v_cmp_le_u32_e32 vcc, v163, v213
	v_subrev_u32_e32 v163, 53, v162
	s_nop 0
	v_cndmask_b32_e32 v69, v229, v69, vcc
	v_cmp_le_u32_e32 vcc, v163, v213
	v_subrev_u32_e32 v163, 52, v162
	s_nop 0
	v_cndmask_b32_e32 v70, v229, v70, vcc
	v_cmp_le_u32_e32 vcc, v163, v213
	v_subrev_u32_e32 v163, 47, v162
	s_nop 0
	v_cndmask_b32_e32 v71, v229, v71, vcc
	v_cmp_le_u32_e32 vcc, v163, v213
	v_subrev_u32_e32 v163, 46, v162
	s_nop 0
	v_cndmask_b32_e32 v72, v229, v72, vcc
	v_cmp_le_u32_e32 vcc, v163, v213
	v_subrev_u32_e32 v163, 45, v162
	s_nop 0
	v_cndmask_b32_e32 v73, v229, v73, vcc
	v_cmp_le_u32_e32 vcc, v163, v213
	v_subrev_u32_e32 v163, 44, v162
	s_nop 0
	v_cndmask_b32_e32 v74, v229, v74, vcc
	v_cmp_le_u32_e32 vcc, v163, v213
	v_subrev_u32_e32 v163, 39, v162
	s_nop 0
	v_cndmask_b32_e32 v75, v229, v75, vcc
	v_cmp_le_u32_e32 vcc, v163, v213
	v_subrev_u32_e32 v163, 38, v162
	s_nop 0
	v_cndmask_b32_e32 v76, v229, v76, vcc
	v_cmp_le_u32_e32 vcc, v163, v213
	v_subrev_u32_e32 v163, 37, v162
	s_nop 0
	v_cndmask_b32_e32 v77, v229, v77, vcc
	v_cmp_le_u32_e32 vcc, v163, v213
	v_subrev_u32_e32 v163, 36, v162
	s_nop 0
	v_cndmask_b32_e32 v78, v229, v78, vcc
	v_cmp_le_u32_e32 vcc, v163, v213
	v_subrev_u32_e32 v163, 31, v162
	s_nop 0
	v_cndmask_b32_e32 v79, v229, v79, vcc
	v_cmp_le_u32_e32 vcc, v163, v213
	v_subrev_u32_e32 v163, 30, v162
	s_nop 0
	v_cndmask_b32_e32 v80, v229, v80, vcc
	v_cmp_le_u32_e32 vcc, v163, v213
	v_subrev_u32_e32 v163, 29, v162
	s_nop 0
	v_cndmask_b32_e32 v81, v229, v81, vcc
	v_cmp_le_u32_e32 vcc, v163, v213
	v_subrev_u32_e32 v163, 28, v162
	s_nop 0
	v_cndmask_b32_e32 v82, v229, v82, vcc
	v_cmp_le_u32_e32 vcc, v163, v213
	v_subrev_u32_e32 v163, 23, v162
	s_nop 0
	v_cndmask_b32_e32 v83, v229, v83, vcc
	v_cmp_le_u32_e32 vcc, v163, v213
	v_subrev_u32_e32 v163, 22, v162
	s_nop 0
	v_cndmask_b32_e32 v84, v229, v84, vcc
	v_cmp_le_u32_e32 vcc, v163, v213
	v_subrev_u32_e32 v163, 21, v162
	s_nop 0
	v_cndmask_b32_e32 v85, v229, v85, vcc
	v_cmp_le_u32_e32 vcc, v163, v213
	v_subrev_u32_e32 v163, 20, v162
	s_nop 0
	v_cndmask_b32_e32 v86, v229, v86, vcc
	v_cmp_le_u32_e32 vcc, v163, v213
	v_add_u32_e32 v163, -15, v162
	s_nop 0
	v_cndmask_b32_e32 v87, v229, v87, vcc
	v_cmp_le_u32_e32 vcc, v163, v213
	v_add_u32_e32 v163, -14, v162
	s_nop 0
	v_cndmask_b32_e32 v88, v229, v88, vcc
	v_cmp_le_u32_e32 vcc, v163, v213
	v_add_u32_e32 v163, -13, v162
	s_nop 0
	v_cndmask_b32_e32 v89, v229, v89, vcc
	v_cmp_le_u32_e32 vcc, v163, v213
	v_add_u32_e32 v163, -12, v162
	s_nop 0
	v_cndmask_b32_e32 v90, v229, v90, vcc
	v_cmp_le_u32_e32 vcc, v163, v213
	v_add_u32_e32 v163, -7, v162
	s_nop 0
	v_cndmask_b32_e32 v91, v229, v91, vcc
	v_cmp_le_u32_e32 vcc, v163, v213
	v_add_u32_e32 v163, -6, v162
	s_nop 0
	v_cndmask_b32_e32 v92, v229, v92, vcc
	v_cmp_le_u32_e32 vcc, v163, v213
	v_add_u32_e32 v163, -5, v162
	v_add_u32_e32 v162, -4, v162
	v_cndmask_b32_e32 v93, v229, v93, vcc
	v_cmp_le_u32_e32 vcc, v163, v213
	s_nop 1
	v_cndmask_b32_e32 v94, v229, v94, vcc
	v_cmp_le_u32_e32 vcc, v162, v213
	s_nop 1
	v_cndmask_b32_e32 v95, v229, v95, vcc

.Lda1_stage:
	s_mul_i32 s8, s16, 0x4400
	v_add_u32_e32 v162, s8, v175
	s_cmp_lt_u32 s15, s12
	s_waitcnt vmcnt(3)
	ds_write_b128 v162, v[144:147]
	s_waitcnt vmcnt(2)
	ds_write_b128 v162, v[148:151] offset:8704
	s_waitcnt vmcnt(1)
	ds_write2_b64 v208, v[156:157], v[158:159] offset1:2
	v_add_u32_e32 v144, 0x2000, v208
	s_cselect_b32 s9, s15, s14
	s_waitcnt vmcnt(0)
	ds_write2_b64 v144, v[152:153], v[154:155] offset0:128 offset1:130
	s_lshl_b32 s9, s9, 6
	v_lshl_add_u64 v[152:153], s[4:5], 1, v[196:197]
	v_mad_u64_u32 v[144:145], s[10:11], s9, v228, v[194:195]
	s_or_b32 s9, s9, 32
	v_add_co_u32_e32 v154, vcc, 0x80000, v152
	v_mad_u64_u32 v[148:149], s[10:11], s9, v228, v[194:195]
	s_nop 0
	v_addc_co_u32_e32 v155, vcc, 0, v153, vcc
	s_waitcnt lgkmcnt(0)
	s_barrier
	global_load_dwordx4 v[144:147], v[144:145], off
	s_nop 0
	global_load_dwordx4 v[148:151], v[148:149], off
	s_nop 0
	global_load_dwordx4 v[156:159], v[152:153], off
	s_nop 0
	global_load_dwordx4 v[152:155], v[154:155], off
	s_add_i32 s4, s13, 34
	v_cmp_le_u32_e32 vcc, s4, v212
	s_mov_b32 s98, s8
	s_and_b64 s[100:101], s[6:7], vcc
	s_cmp_eq_u32 s99, 0
	s_cbranch_scc0 .Lda2_soft
.Lda2_qk:
	s_and_saveexec_b64 s[6:7], s[100:101]
	s_cbranch_execz .LBB0_215
	s_setprio 1
	v_add3_u32 v162, v203, s98, v204
	ds_read_b128 v[80:83], v162
	ds_read_b128 v[84:87], v162 offset:32
	ds_read_b128 v[88:91], v162 offset:64
	ds_read_b128 v[92:95], v162 offset:96
	ds_read_b128 v[222:225], v162 offset:8704
	ds_read_b128 v[236:239], v162 offset:8736
	ds_read_b128 v[240:243], v162 offset:8768
	ds_read_b128 v[244:247], v162 offset:8800
	s_waitcnt lgkmcnt(7)
	v_mfma_f32_32x32x16_bf16 v[64:79], v[80:83], v[128:131], 0
	s_waitcnt lgkmcnt(6)
	v_mfma_f32_32x32x16_bf16 v[64:79], v[84:87], v[132:135], v[64:79]
	s_waitcnt lgkmcnt(5)
	v_mfma_f32_32x32x16_bf16 v[64:79], v[88:91], v[136:139], v[64:79]
	s_waitcnt lgkmcnt(4)
	v_mfma_f32_32x32x16_bf16 v[64:79], v[92:95], v[140:143], v[64:79]
	s_waitcnt lgkmcnt(3)
	v_mfma_f32_32x32x16_bf16 v[80:95], v[222:225], v[128:131], 0
	s_waitcnt lgkmcnt(2)
	v_mfma_f32_32x32x16_bf16 v[80:95], v[236:239], v[132:135], v[80:95]
	s_waitcnt lgkmcnt(1)
	v_mfma_f32_32x32x16_bf16 v[80:95], v[240:243], v[136:139], v[80:95]
	s_waitcnt lgkmcnt(0)
	v_mfma_f32_32x32x16_bf16 v[80:95], v[244:247], v[140:143], v[80:95]
	s_setprio 0

.Lda2_soft:
	s_add_i32 s4, s13, 1
	v_cmp_le_u32_e32 vcc, s4, v214
	s_and_saveexec_b64 s[6:7], vcc
	s_cbranch_execz .LBB0_204
	s_add_i32 s4, s13, 64
	v_cmp_gt_u32_e32 vcc, s4, v212
	s_and_saveexec_b64 s[8:9], vcc
	s_cbranch_execz .LBB0_218
	v_add_u32_e32 v162, s13, v180
	v_add_u32_e32 v163, 1, v162
	v_cmp_lt_u32_e32 vcc, v163, v213
	s_nop 1
	v_cndmask_b32_e32 v97, v229, v97, vcc
	v_cmp_le_u32_e32 vcc, v163, v213
	v_add_u32_e32 v163, 3, v162
	s_nop 0
	v_cndmask_b32_e32 v96, v229, v96, vcc
	v_cmp_le_u32_e32 vcc, v163, v213
	v_add_u32_e32 v163, 4, v162
	s_nop 0
	v_cndmask_b32_e32 v98, v229, v98, vcc
	v_cmp_le_u32_e32 vcc, v163, v213
	v_add_u32_e32 v163, 9, v162
	s_nop 0
	v_cndmask_b32_e32 v99, v229, v99, vcc
	v_cmp_le_u32_e32 vcc, v163, v213
	v_add_u32_e32 v163, 10, v162
	s_nop 0
	v_cndmask_b32_e32 v100, v229, v100, vcc
	v_cmp_le_u32_e32 vcc, v163, v213
	v_add_u32_e32 v163, 11, v162
	s_nop 0
	v_cndmask_b32_e32 v101, v229, v101, vcc
	v_cmp_le_u32_e32 vcc, v163, v213
	v_add_u32_e32 v163, 12, v162
	s_nop 0
	v_cndmask_b32_e32 v102, v229, v102, vcc
	v_cmp_le_u32_e32 vcc, v163, v213
	v_add_u32_e32 v163, 17, v162
	s_nop 0
	v_cndmask_b32_e32 v103, v229, v103, vcc
	v_cmp_le_u32_e32 vcc, v163, v213
	v_add_u32_e32 v163, 18, v162
	s_nop 0
	v_cndmask_b32_e32 v104, v229, v104, vcc
	v_cmp_le_u32_e32 vcc, v163, v213
	v_add_u32_e32 v163, 19, v162
	s_nop 0
	v_cndmask_b32_e32 v105, v229, v105, vcc
	v_cmp_le_u32_e32 vcc, v163, v213
	v_add_u32_e32 v163, 20, v162
	s_nop 0
	v_cndmask_b32_e32 v106, v229, v106, vcc
	v_cmp_le_u32_e32 vcc, v163, v213
	v_add_u32_e32 v163, 25, v162
	s_nop 0
	v_cndmask_b32_e32 v107, v229, v107, vcc
	v_cmp_le_u32_e32 vcc, v163, v213
	v_add_u32_e32 v163, 26, v162
	s_nop 0
	v_cndmask_b32_e32 v108, v229, v108, vcc
	v_cmp_le_u32_e32 vcc, v163, v213
	v_add_u32_e32 v163, 27, v162
	s_nop 0
	v_cndmask_b32_e32 v109, v229, v109, vcc
	v_cmp_le_u32_e32 vcc, v163, v213
	v_add_u32_e32 v163, 28, v162
	s_nop 0
	v_cndmask_b32_e32 v110, v229, v110, vcc
	v_cmp_le_u32_e32 vcc, v163, v213
	v_add_u32_e32 v163, 33, v162
	s_nop 0
	v_cndmask_b32_e32 v111, v229, v111, vcc
	v_cmp_le_u32_e32 vcc, v163, v213
	v_add_u32_e32 v163, 34, v162
	s_nop 0
	v_cndmask_b32_e32 v112, v229, v112, vcc
	v_cmp_le_u32_e32 vcc, v163, v213
	v_add_u32_e32 v163, 35, v162
	s_nop 0
	v_cndmask_b32_e32 v113, v229, v113, vcc
	v_cmp_le_u32_e32 vcc, v163, v213
	v_add_u32_e32 v163, 36, v162
	s_nop 0
	v_cndmask_b32_e32 v114, v229, v114, vcc
	v_cmp_le_u32_e32 vcc, v163, v213
	v_add_u32_e32 v163, 41, v162
	s_nop 0
	v_cndmask_b32_e32 v115, v229, v115, vcc
	v_cmp_le_u32_e32 vcc, v163, v213
	v_add_u32_e32 v163, 42, v162
	s_nop 0
	v_cndmask_b32_e32 v116, v229, v116, vcc
	v_cmp_le_u32_e32 vcc, v163, v213
	v_add_u32_e32 v163, 43, v162
	s_nop 0
	v_cndmask_b32_e32 v117, v229, v117, vcc
	v_cmp_le_u32_e32 vcc, v163, v213
	v_add_u32_e32 v163, 44, v162
	s_nop 0
	v_cndmask_b32_e32 v118, v229, v118, vcc
	v_cmp_le_u32_e32 vcc, v163, v213
	v_add_u32_e32 v163, 49, v162
	s_nop 0
	v_cndmask_b32_e32 v119, v229, v119, vcc
	v_cmp_le_u32_e32 vcc, v163, v213
	v_add_u32_e32 v163, 50, v162
	s_nop 0
	v_cndmask_b32_e32 v120, v229, v120, vcc
	v_cmp_le_u32_e32 vcc, v163, v213
	v_add_u32_e32 v163, 51, v162
	s_nop 0
	v_cndmask_b32_e32 v121, v229, v121, vcc
	v_cmp_le_u32_e32 vcc, v163, v213
	v_add_u32_e32 v163, 52, v162
	s_nop 0
	v_cndmask_b32_e32 v122, v229, v122, vcc
	v_cmp_le_u32_e32 vcc, v163, v213
	v_add_u32_e32 v163, 57, v162
	s_nop 0
	v_cndmask_b32_e32 v123, v229, v123, vcc
	v_cmp_le_u32_e32 vcc, v163, v213
	v_add_u32_e32 v163, 58, v162
	s_nop 0
	v_cndmask_b32_e32 v124, v229, v124, vcc
	v_cmp_le_u32_e32 vcc, v163, v213
	v_add_u32_e32 v163, 59, v162
	v_add_u32_e32 v162, 60, v162
	v_cndmask_b32_e32 v125, v229, v125, vcc
	v_cmp_le_u32_e32 vcc, v163, v213
	s_nop 1
	v_cndmask_b32_e32 v126, v229, v126, vcc
	v_cmp_le_u32_e32 vcc, v162, v213
	s_nop 1
	v_cndmask_b32_e32 v127, v229, v127, vcc

	.amdhsa_kernel _Z4mega6Params
		.amdhsa_group_segment_fixed_size 0
		.amdhsa_private_segment_fixed_size 0
		.amdhsa_kernarg_size 528
		.amdhsa_user_sgpr_count 2
		.amdhsa_user_sgpr_dispatch_ptr 0
		.amdhsa_user_sgpr_queue_ptr 0
		.amdhsa_user_sgpr_kernarg_segment_ptr 1
		.amdhsa_user_sgpr_dispatch_id 0
		.amdhsa_user_sgpr_kernarg_preload_length 0
		.amdhsa_user_sgpr_kernarg_preload_offset 0
		.amdhsa_user_sgpr_private_segment_size 0
		.amdhsa_uses_dynamic_stack 0
		.amdhsa_enable_private_segment 0
		.amdhsa_system_sgpr_workgroup_id_x 1
		.amdhsa_system_sgpr_workgroup_id_y 0
		.amdhsa_system_sgpr_workgroup_id_z 0
		.amdhsa_system_sgpr_workgroup_info 0
		.amdhsa_system_vgpr_workitem_id 2
		.amdhsa_next_free_vgpr 256
		.amdhsa_next_free_sgpr 102
		.amdhsa_accum_offset 256
		.amdhsa_reserve_vcc 1
		.amdhsa_float_round_mode_32 0
		.amdhsa_float_round_mode_16_64 0
		.amdhsa_float_denorm_mode_32 3
		.amdhsa_float_denorm_mode_16_64 3
		.amdhsa_dx10_clamp 1
		.amdhsa_ieee_mode 1
		.amdhsa_fp16_overflow 0
		.amdhsa_tg_split 0
		.amdhsa_exception_fp_ieee_invalid_op 0
		.amdhsa_exception_fp_denorm_src 0
		.amdhsa_exception_fp_ieee_div_zero 0
		.amdhsa_exception_fp_ieee_overflow 0
		.amdhsa_exception_fp_ieee_underflow 0
		.amdhsa_exception_fp_ieee_inexact 0
		.amdhsa_exception_int_div_zero 0
	.end_amdhsa_kernel

amdhsa.kernels:
  - .agpr_count:     0
    .args:
      - .offset:         0
        .size:           272
        .value_kind:     by_value
      - .offset:         272
        .size:           4
        .value_kind:     hidden_block_count_x
      - .offset:         276
        .size:           4
        .value_kind:     hidden_block_count_y
      - .offset:         280
        .size:           4
        .value_kind:     hidden_block_count_z
      - .offset:         284
        .size:           2
        .value_kind:     hidden_group_size_x
      - .offset:         286
        .size:           2
        .value_kind:     hidden_group_size_y
      - .offset:         288
        .size:           2
        .value_kind:     hidden_group_size_z
      - .offset:         290
        .size:           2
        .value_kind:     hidden_remainder_x
      - .offset:         292
        .size:           2
        .value_kind:     hidden_remainder_y
      - .offset:         294
        .size:           2
        .value_kind:     hidden_remainder_z
      - .offset:         312
        .size:           8
        .value_kind:     hidden_global_offset_x
      - .offset:         320
        .size:           8
        .value_kind:     hidden_global_offset_y
      - .offset:         328
        .size:           8
        .value_kind:     hidden_global_offset_z
      - .offset:         336
        .size:           2
        .value_kind:     hidden_grid_dims
      - .offset:         360
        .size:           8
        .value_kind:     hidden_multigrid_sync_arg
      - .offset:         392
        .size:           4
        .value_kind:     hidden_dynamic_lds_size
    .group_segment_fixed_size: 0
    .kernarg_segment_align: 8
    .kernarg_segment_size: 528
    .language:       OpenCL C
    .language_version:
      - 2
      - 0
    .max_flat_workgroup_size: 512
    .name:           _Z4mega6Params
    .private_segment_fixed_size: 0
    .sgpr_count:     108
    .sgpr_spill_count: 252
    .symbol:         _Z4mega6Params.kd
    .uniform_work_group_size: 1
    .uses_dynamic_stack: false
    .vgpr_count:     256
    .vgpr_spill_count: 0
    .wavefront_size: 64
